# attention tile loop: removed the dead M0 save/restore pair around each of the 8 LDS-DMA blocks (16 SALU fewer per wave-step), on top of v58
# speedup vs baseline: 1.0016x; 1.0016x over previous
; #define ATT_WAIT_BAR() asm volatile("s_waitcnt vmcnt(0) lgkmcnt(0)\n\ts_barrier" ::: "memory")
; #define ATT_SB() __builtin_amdgcn_sched_barrier(0)
; #define A16_VLD(v, g) do { const LAS unsigned char* a_ = vbp[(g) & 3] + vso + ((g) >> 4) * 16384 + (((g) & 15) >> 2) * 1024; v[0] = vtr(a_); v[1] = vtr(a_ + 8192); } while (0)
; #define A16_GAP(i) do { A16_EL(i) = __builtin_amdgcn_exp2f(A16_EL(i)); \
;                 if ((i) > 0) { if ((((i) - 1) >> 2) & 1) s1 += A16_EL((i) - 1); else s0 += A16_EL((i) - 1); } asm volatile("" : "+v"(s0), "+v"(s1)); } while (0)
; __device__ __forceinline__ void attn_core16(f32x4 (&O)[16][2], float (&lq)[2], const bf16_t* Qw, int q_pitch, const bf16_t* Kh, const bf16_t* Vh, int kv_pitch,
;                                             int NT, int nt_act, int kch0, float negb, LAS unsigned char* ring, int wid) {
;     ...
;         ATT_WAIT_BAR();
;         if (t < nt_act) {
;             const bool more = (t + 1 < nt_act);
;             const int vso = (t & 1) * SLOTB;
;             s16x4 vv[3][2];
;     ...
;             A16_VLD(vv[0], 0);
;             ATT_SB();
;             A16_QK(t + 1, 1, t);
;             ATT_SB();
;             A16_VLD(vv[1], 1);
;             float s0 = 0.f, s1 = 0.f;
;     ...
; #pragma unroll
;             for (int g = 0; g < 32; ++g) {
;                 if (g + 2 < 32) A16_VLD(vv[(g + 2) % 3], g + 2);
;                 ATT_SB();
;                 O[g & 15][0] = __builtin_amdgcn_mfma_f32_16x16x32_bf16(A16_VF(vv[g % 3]), __builtin_bit_cast(bf16x8, pw[g >> 4][0]), O[g & 15][0], 0, 0, 0);
;                 O[g & 15][1] = __builtin_amdgcn_mfma_f32_16x16x32_bf16(A16_VF(vv[g % 3]), __builtin_bit_cast(bf16x8, pw[g >> 4][1]), O[g & 15][1], 0, 0, 0);
;                 A16_GAP(g);
.LBB0_685:
	s_waitcnt vmcnt(0) lgkmcnt(0)
	s_barrier
	s_add_i32 s20, s0, 1
	s_cmp_ge_u32 s0, s73
	s_cbranch_scc1 .LBB0_687
	s_and_b32 s80, s72, 0x10000
	v_add_u32_e32 v2, s80, v214
	ds_read_b128 v[188:191], v2
	ds_read_b128 v[192:195], v2 offset:8192
	s_add_i32 s48, s72, 0xffff0000
	s_and_b32 s50, s48, 0x10000
	v_add_u32_e32 v0, s50, v216
	ds_read_b64_tr_b16 v[220:221], v0 offset:32768
	ds_read_b64_tr_b16 v[222:223], v0 offset:40960
	s_add_i32 s0, s0, 2
	s_min_u32 vcc_lo, s0, s21
	s_min_u32 s0, s20, s21
	s_lshl_b64 s[70:71], s[0:1], 18
	s_add_u32 s70, s38, s70
	s_mov_b32 vcc_hi, s1
	ds_read_b128 v[200:203], v2 offset:16384
	s_addc_u32 s71, s39, s71
	s_add_i32 s0, s12, s80
	s_lshl_b64 vcc, vcc, 18
	s_add_u32 s54, s18, vcc_lo
	s_addc_u32 s55, s19, vcc_hi
	s_add_i32 vcc_lo, s13, s50
	s_waitcnt lgkmcnt(4)
	v_mfma_f32_16x16x32_bf16 v[196:199], v[188:191], v[136:139], v[168:171]
	s_mov_b32 m0, vcc_lo
	s_nop 0
	global_load_lds_dwordx4 v212, s[54:55]
	v_mfma_f32_16x16x32_bf16 v[188:191], v[188:191], v[152:155], v[168:171]
	ds_read_b128 v[204:207], v2 offset:24576
	s_add_u32 s48, s54, 0x80
	s_waitcnt lgkmcnt(2)
	v_mfma_f32_16x16x32_bf16 v[224:227], v[192:195], v[136:139], v[168:171]
	s_addc_u32 s49, s55, 0
	s_add_i32 vcc_hi, vcc_lo, 0x400
	s_mov_b32 m0, vcc_hi
	s_nop 0
	global_load_lds_dwordx4 v212, s[48:49]
	v_mfma_f32_16x16x32_bf16 v[192:195], v[192:195], v[152:155], v[168:171]
	v_add_u32_e32 v3, s80, v215
	ds_read_b128 v[230:233], v3
	s_add_u32 s48, s54, 0x100
	s_waitcnt lgkmcnt(2)
	v_mfma_f32_16x16x32_bf16 v[234:237], v[200:203], v[136:139], v[168:171]
	s_addc_u32 s49, s55, 0
	s_add_i32 s9, vcc_lo, 0x800
	s_mov_b32 m0, s9
	s_nop 0
	global_load_lds_dwordx4 v212, s[48:49]
	v_mfma_f32_16x16x32_bf16 v[200:203], v[200:203], v[152:155], v[168:171]
	ds_read_b128 v[238:241], v3 offset:8192
	s_add_u32 s48, s54, 0x180
	s_waitcnt lgkmcnt(2)
	v_mfma_f32_16x16x32_bf16 v[242:245], v[204:207], v[136:139], v[168:171]
	s_addc_u32 s49, s55, 0
	s_add_i32 s9, vcc_lo, 0xc00
	s_mov_b32 m0, s9
	s_nop 0
	global_load_lds_dwordx4 v212, s[48:49]
	v_mfma_f32_16x16x32_bf16 v[204:207], v[204:207], v[152:155], v[168:171]
	ds_read_b128 v[246:249], v3 offset:16384
	s_waitcnt lgkmcnt(2)
	v_mfma_f32_16x16x32_bf16 v[196:199], v[230:233], v[140:143], v[196:199]
	s_mov_b32 m0, s0
	s_nop 0
	global_load_lds_dwordx4 v213, s[70:71]
	v_mfma_f32_16x16x32_bf16 v[188:191], v[230:233], v[156:159], v[188:191]
	ds_read_b128 v[230:233], v3 offset:24576
	s_add_u32 s48, s70, 0x80
	s_waitcnt lgkmcnt(2)
	v_mfma_f32_16x16x32_bf16 v[192:195], v[238:241], v[156:159], v[192:195]
	s_addc_u32 s49, s71, 0
	s_add_i32 s9, s0, 0x400
	s_mov_b32 m0, s9
	s_nop 0
	global_load_lds_dwordx4 v213, s[48:49]
	v_mfma_f32_16x16x32_bf16 v[224:227], v[238:241], v[140:143], v[224:227]
	ds_read_b128 v[238:241], v2 offset:1024
	s_add_u32 s48, s70, 0x100
	s_waitcnt lgkmcnt(2)
	v_mfma_f32_16x16x32_bf16 v[234:237], v[246:249], v[140:143], v[234:237]
	s_addc_u32 s49, s71, 0
	s_add_i32 s9, s0, 0x800
	s_mov_b32 m0, s9
	s_nop 0
	global_load_lds_dwordx4 v213, s[48:49]
	v_mfma_f32_16x16x32_bf16 v[200:203], v[246:249], v[156:159], v[200:203]
	ds_read_b128 v[246:249], v2 offset:9216
	s_add_u32 s48, s70, 0x180
	s_waitcnt lgkmcnt(2)
	v_mfma_f32_16x16x32_bf16 v[204:207], v[230:233], v[156:159], v[204:207]
	s_addc_u32 s49, s71, 0
	s_addk_i32 s0, 0xc00
	s_mov_b32 m0, s0
	s_nop 0
	global_load_lds_dwordx4 v213, s[48:49]
	v_mfma_f32_16x16x32_bf16 v[242:245], v[230:233], v[140:143], v[242:245]
	ds_read_b128 v[230:233], v2 offset:17408
	s_waitcnt lgkmcnt(2)
	v_mfma_f32_16x16x32_bf16 v[196:199], v[238:241], v[144:147], v[196:199]
	v_mfma_f32_16x16x32_bf16 v[188:191], v[238:241], v[160:163], v[188:191]
	ds_read_b128 v[238:241], v2 offset:25600
	s_waitcnt lgkmcnt(2)
	v_mfma_f32_16x16x32_bf16 v[192:195], v[246:249], v[160:163], v[192:195]
	v_mfma_f32_16x16x32_bf16 v[224:227], v[246:249], v[144:147], v[224:227]
	ds_read_b128 v[246:249], v3 offset:1024
	s_waitcnt lgkmcnt(2)
	v_mfma_f32_16x16x32_bf16 v[234:237], v[230:233], v[144:147], v[234:237]
	v_mfma_f32_16x16x32_bf16 v[230:233], v[230:233], v[160:163], v[200:203]
	s_nop 2
	ds_read_b128 v[200:203], v3 offset:9216
	s_waitcnt lgkmcnt(2)
	v_mfma_f32_16x16x32_bf16 v[242:245], v[238:241], v[144:147], v[242:245]
	v_mfma_f32_16x16x32_bf16 v[238:241], v[238:241], v[160:163], v[204:207]
	s_waitcnt lgkmcnt(1)
	v_mfma_f32_16x16x32_bf16 v[250:253], v[246:249], v[148:151], v[196:199]
	s_nop 2
	ds_read_b128 v[196:199], v3 offset:17408
	v_mfma_f32_16x16x32_bf16 v[246:249], v[246:249], v[164:167], v[188:191]
	s_nop 2
	ds_read_b128 v[188:191], v3 offset:25600
	s_waitcnt lgkmcnt(2)
	v_mfma_f32_16x16x32_bf16 v[224:227], v[200:203], v[148:151], v[224:227]
	v_mfma_f32_16x16x32_bf16 v[204:207], v[200:203], v[164:167], v[192:195]
	s_waitcnt lgkmcnt(1)
	v_mfma_f32_16x16x32_bf16 v[200:203], v[196:199], v[148:151], v[234:237]
	v_mfma_f32_16x16x32_bf16 v[196:199], v[196:199], v[164:167], v[230:233]
	s_waitcnt lgkmcnt(0)
	v_mfma_f32_16x16x32_bf16 v[192:195], v[188:191], v[148:151], v[242:245]
	v_mfma_f32_16x16x32_bf16 v[188:191], v[188:191], v[164:167], v[238:241]
	v_add_u32_e32 v229, s50, v217
	s_nop 1
	v_add_u32_e32 v238, s50, v218
	ds_read_b64_tr_b16 v[230:231], v229 offset:32768
	ds_read_b64_tr_b16 v[232:233], v229 offset:40960
	ds_read_b64_tr_b16 v[234:235], v238 offset:32768
	ds_read_b64_tr_b16 v[236:237], v238 offset:40960
	v_mfma_f32_16x16x32_bf16 v[68:71], v[220:223], v[184:187], v[68:71]
	v_mov_b32_e32 v239, 0
	v_mov_b32_e32 v240, 0
	v_exp_f32_e32 v2, v250
	v_mfma_f32_16x16x32_bf16 v[132:135], v[220:223], v[180:183], v[132:135]
	v_add_u32_e32 v241, s50, v219
	ds_read_b64_tr_b16 v[220:221], v241 offset:32768
	ds_read_b64_tr_b16 v[222:223], v241 offset:40960
	s_waitcnt lgkmcnt(4)
; #define ATT_SB() __builtin_amdgcn_sched_barrier(0)
; #define A16_VLD(v, g) do { const LAS unsigned char* a_ = vbp[(g) & 3] + vso + ((g) >> 4) * 16384 + (((g) & 15) >> 2) * 1024; v[0] = vtr(a_); v[1] = vtr(a_ + 8192); } while (0)
; #define A16_GAP(i) do { A16_EL(i) = __builtin_amdgcn_exp2f(A16_EL(i)); \
;                 if ((i) > 0) { if ((((i) - 1) >> 2) & 1) s1 += A16_EL((i) - 1); else s0 += A16_EL((i) - 1); } asm volatile("" : "+v"(s0), "+v"(s1)); } while (0)
; __device__ __forceinline__ void attn_core16(f32x4 (&O)[16][2], float (&lq)[2], const bf16_t* Qw, int q_pitch, const bf16_t* Kh, const bf16_t* Vh, int kv_pitch,
;                                             int NT, int nt_act, int kch0, float negb, LAS unsigned char* ring, int wid) {
;     ...
;             A16_VLD(vv[0], 0);
;             ATT_SB();
;             A16_QK(t + 1, 1, t);
;             ATT_SB();
;             A16_VLD(vv[1], 1);
;             float s0 = 0.f, s1 = 0.f;
;     ...
; #pragma unroll
;             for (int g = 0; g < 32; ++g) {
;                 if (g + 2 < 32) A16_VLD(vv[(g + 2) % 3], g + 2);
;                 ATT_SB();
;                 O[g & 15][0] = __builtin_amdgcn_mfma_f32_16x16x32_bf16(A16_VF(vv[g % 3]), __builtin_bit_cast(bf16x8, pw[g >> 4][0]), O[g & 15][0], 0, 0, 0);
;                 O[g & 15][1] = __builtin_amdgcn_mfma_f32_16x16x32_bf16(A16_VF(vv[g % 3]), __builtin_bit_cast(bf16x8, pw[g >> 4][1]), O[g & 15][1], 0, 0, 0);
;                 A16_GAP(g);
;                 ATT_SB();
;             }
	v_mfma_f32_16x16x32_bf16 v[128:131], v[230:233], v[180:183], v[128:131]
	v_add_f32_e32 v239, v2, v239
	v_exp_f32_e32 v3, v251
	v_mfma_f32_16x16x32_bf16 v[64:67], v[230:233], v[184:187], v[64:67]
	ds_read_b64_tr_b16 v[230:231], v0 offset:33792
	ds_read_b64_tr_b16 v[232:233], v0 offset:41984
	s_waitcnt lgkmcnt(4)
	v_mfma_f32_16x16x32_bf16 v[60:63], v[234:237], v[184:187], v[60:63]
	v_add_f32_e32 v239, v3, v239
	v_exp_f32_e32 v242, v252
	v_mfma_f32_16x16x32_bf16 v[124:127], v[234:237], v[180:183], v[124:127]
	ds_read_b64_tr_b16 v[234:235], v229 offset:33792
	ds_read_b64_tr_b16 v[236:237], v229 offset:41984
	s_waitcnt lgkmcnt(4)
	v_mfma_f32_16x16x32_bf16 v[120:123], v[220:223], v[180:183], v[120:123]
	v_add_f32_e32 v239, v242, v239
	v_exp_f32_e32 v243, v253
	v_mfma_f32_16x16x32_bf16 v[56:59], v[220:223], v[184:187], v[56:59]
	ds_read_b64_tr_b16 v[220:221], v238 offset:33792
	ds_read_b64_tr_b16 v[222:223], v238 offset:41984
	s_waitcnt lgkmcnt(4)
	v_mfma_f32_16x16x32_bf16 v[52:55], v[230:233], v[184:187], v[52:55]
	v_add_f32_e32 v239, v243, v239
	v_exp_f32_e32 v244, v246
	v_mfma_f32_16x16x32_bf16 v[116:119], v[230:233], v[180:183], v[116:119]
	ds_read_b64_tr_b16 v[230:231], v241 offset:33792
	ds_read_b64_tr_b16 v[232:233], v241 offset:41984
	s_waitcnt lgkmcnt(4)
	v_mfma_f32_16x16x32_bf16 v[112:115], v[234:237], v[180:183], v[112:115]
	v_add_f32_e32 v240, v244, v240
	v_exp_f32_e32 v245, v247
	v_mfma_f32_16x16x32_bf16 v[48:51], v[234:237], v[184:187], v[48:51]
	ds_read_b64_tr_b16 v[234:235], v0 offset:34816
	ds_read_b64_tr_b16 v[236:237], v0 offset:43008
	s_waitcnt lgkmcnt(4)
	v_mfma_f32_16x16x32_bf16 v[44:47], v[220:223], v[184:187], v[44:47]
	v_add_f32_e32 v240, v245, v240
	v_exp_f32_e32 v246, v248
	v_mfma_f32_16x16x32_bf16 v[108:111], v[220:223], v[180:183], v[108:111]
	ds_read_b64_tr_b16 v[220:221], v229 offset:34816
	ds_read_b64_tr_b16 v[222:223], v229 offset:43008
	s_waitcnt lgkmcnt(4)
	v_mfma_f32_16x16x32_bf16 v[104:107], v[230:233], v[180:183], v[104:107]
	v_add_f32_e32 v240, v246, v240
	v_exp_f32_e32 v247, v249
	v_mfma_f32_16x16x32_bf16 v[40:43], v[230:233], v[184:187], v[40:43]
	ds_read_b64_tr_b16 v[230:231], v238 offset:34816
	ds_read_b64_tr_b16 v[232:233], v238 offset:43008
	s_waitcnt lgkmcnt(4)
	v_mfma_f32_16x16x32_bf16 v[36:39], v[234:237], v[184:187], v[36:39]
	v_add_f32_e32 v240, v247, v240
	v_exp_f32_e32 v248, v224
	v_mfma_f32_16x16x32_bf16 v[100:103], v[234:237], v[180:183], v[100:103]
	ds_read_b64_tr_b16 v[234:235], v241 offset:34816
	ds_read_b64_tr_b16 v[236:237], v241 offset:43008
	s_waitcnt lgkmcnt(4)
	v_mfma_f32_16x16x32_bf16 v[96:99], v[220:223], v[180:183], v[96:99]
	v_add_f32_e32 v224, v248, v239
	v_exp_f32_e32 v249, v225
	v_mfma_f32_16x16x32_bf16 v[32:35], v[220:223], v[184:187], v[32:35]
	ds_read_b64_tr_b16 v[220:221], v0 offset:35840
	ds_read_b64_tr_b16 v[222:223], v0 offset:44032
	s_waitcnt lgkmcnt(4)
	v_mfma_f32_16x16x32_bf16 v[28:31], v[230:233], v[184:187], v[28:31]
	v_add_f32_e32 v224, v249, v224
	v_exp_f32_e32 v239, v226
	v_mfma_f32_16x16x32_bf16 v[92:95], v[230:233], v[180:183], v[92:95]
	ds_read_b64_tr_b16 v[230:231], v229 offset:35840
	ds_read_b64_tr_b16 v[232:233], v229 offset:44032
	s_waitcnt lgkmcnt(4)
	v_mfma_f32_16x16x32_bf16 v[88:91], v[234:237], v[180:183], v[88:91]
	v_add_f32_e32 v251, v239, v224
	v_exp_f32_e32 v250, v227
	v_mfma_f32_16x16x32_bf16 v[24:27], v[234:237], v[184:187], v[24:27]
	ds_read_b64_tr_b16 v[224:225], v238 offset:35840
	ds_read_b64_tr_b16 v[226:227], v238 offset:44032
	s_waitcnt lgkmcnt(4)
	v_mfma_f32_16x16x32_bf16 v[20:23], v[220:223], v[184:187], v[20:23]
	v_exp_f32_e32 v234, v204
	v_add_f32_e32 v204, v250, v251
	v_mfma_f32_16x16x32_bf16 v[84:87], v[220:223], v[180:183], v[84:87]
	ds_read_b64_tr_b16 v[220:221], v241 offset:35840
	ds_read_b64_tr_b16 v[222:223], v241 offset:44032
	s_waitcnt lgkmcnt(4)
	v_mfma_f32_16x16x32_bf16 v[80:83], v[230:233], v[180:183], v[80:83]
	v_exp_f32_e32 v235, v205
	v_add_f32_e32 v205, v234, v240
	v_mfma_f32_16x16x32_bf16 v[16:19], v[230:233], v[184:187], v[16:19]
	ds_read_b64_tr_b16 v[230:231], v0 offset:49152
	ds_read_b64_tr_b16 v[232:233], v0 offset:57344
	s_waitcnt lgkmcnt(4)
	v_mfma_f32_16x16x32_bf16 v[12:15], v[224:227], v[184:187], v[12:15]
	v_add_f32_e32 v205, v235, v205
	v_exp_f32_e32 v236, v206
	v_mfma_f32_16x16x32_bf16 v[76:79], v[224:227], v[180:183], v[76:79]
	ds_read_b64_tr_b16 v[224:225], v229 offset:49152
	ds_read_b64_tr_b16 v[226:227], v229 offset:57344
	s_waitcnt lgkmcnt(4)
	v_mfma_f32_16x16x32_bf16 v[8:11], v[220:223], v[184:187], v[8:11]
	v_add_f32_e32 v184, v236, v205
	v_exp_f32_e32 v237, v207
	v_mfma_f32_16x16x32_bf16 v[72:75], v[220:223], v[180:183], v[72:75]
	ds_read_b64_tr_b16 v[180:181], v238 offset:49152
	ds_read_b64_tr_b16 v[182:183], v238 offset:57344
	s_waitcnt lgkmcnt(4)
	v_mfma_f32_16x16x32_bf16 v[68:71], v[230:233], v[176:179], v[68:71]
	v_add_f32_e32 v221, v237, v184
	v_exp_f32_e32 v220, v200
	v_mfma_f32_16x16x32_bf16 v[132:135], v[230:233], v[172:175], v[132:135]
	ds_read_b64_tr_b16 v[184:185], v241 offset:49152
	ds_read_b64_tr_b16 v[186:187], v241 offset:57344
	s_waitcnt lgkmcnt(4)
; #define ATT_SB() __builtin_amdgcn_sched_barrier(0)
; #define A16_PACK() do { _Pragma("unroll") for (int p_ = 0; p_ < 2; ++p_) _Pragma("unroll") for (int h_ = 0; h_ < 2; ++h_) \
;         pw[p_][h_] = (u32x4){pk2(S[2 * p_][h_][0], S[2 * p_][h_][1]), pk2(S[2 * p_][h_][2], S[2 * p_][h_][3]), pk2(S[2 * p_ + 1][h_][0], S[2 * p_ + 1][h_][1]), pk2(S[2 * p_ + 1][h_][2], S[2 * p_ + 1][h_][3])}; } while (0)
; #define A16_VLD(v, g) do { const LAS unsigned char* a_ = vbp[(g) & 3] + vso + ((g) >> 4) * 16384 + (((g) & 15) >> 2) * 1024; v[0] = vtr(a_); v[1] = vtr(a_ + 8192); } while (0)
; #define A16_GAP(i) do { A16_EL(i) = __builtin_amdgcn_exp2f(A16_EL(i)); \
;                 if ((i) > 0) { if ((((i) - 1) >> 2) & 1) s1 += A16_EL((i) - 1); else s0 += A16_EL((i) - 1); } asm volatile("" : "+v"(s0), "+v"(s1)); } while (0)
; __device__ __forceinline__ void attn_core16(f32x4 (&O)[16][2], float (&lq)[2], const bf16_t* Qw, int q_pitch, const bf16_t* Kh, const bf16_t* Vh, int kv_pitch,
;                                             int NT, int nt_act, int kch0, float negb, LAS unsigned char* ring, int wid) {
;     ...
; #pragma unroll
;             for (int g = 0; g < 32; ++g) {
;                 if (g + 2 < 32) A16_VLD(vv[(g + 2) % 3], g + 2);
;                 ATT_SB();
;                 O[g & 15][0] = __builtin_amdgcn_mfma_f32_16x16x32_bf16(A16_VF(vv[g % 3]), __builtin_bit_cast(bf16x8, pw[g >> 4][0]), O[g & 15][0], 0, 0, 0);
;                 O[g & 15][1] = __builtin_amdgcn_mfma_f32_16x16x32_bf16(A16_VF(vv[g % 3]), __builtin_bit_cast(bf16x8, pw[g >> 4][1]), O[g & 15][1], 0, 0, 0);
;                 A16_GAP(g);
;                 ATT_SB();
;             }
;     ...
;             l0 += more ? s0 : 0.f; l1 += more ? (s1 + A16_EL(31)) : 0.f;
;             A16_PACK();
	v_mfma_f32_16x16x32_bf16 v[128:131], v[224:227], v[172:175], v[128:131]
	v_add_f32_e32 v200, v220, v204
	v_exp_f32_e32 v222, v201
	v_mfma_f32_16x16x32_bf16 v[64:67], v[224:227], v[176:179], v[64:67]
	ds_read_b64_tr_b16 v[204:205], v0 offset:50176
	ds_read_b64_tr_b16 v[206:207], v0 offset:58368
	s_waitcnt lgkmcnt(4)
	v_mfma_f32_16x16x32_bf16 v[60:63], v[180:183], v[176:179], v[60:63]
	v_add_f32_e32 v200, v222, v200
	v_exp_f32_e32 v223, v202
	v_mfma_f32_16x16x32_bf16 v[124:127], v[180:183], v[172:175], v[124:127]
	ds_read_b64_tr_b16 v[180:181], v229 offset:50176
	ds_read_b64_tr_b16 v[182:183], v229 offset:58368
	s_waitcnt lgkmcnt(4)
	v_mfma_f32_16x16x32_bf16 v[120:123], v[184:187], v[172:175], v[120:123]
	v_add_f32_e32 v200, v223, v200
	v_exp_f32_e32 v224, v203
	v_mfma_f32_16x16x32_bf16 v[56:59], v[184:187], v[176:179], v[56:59]
	ds_read_b64_tr_b16 v[184:185], v238 offset:50176
	ds_read_b64_tr_b16 v[186:187], v238 offset:58368
	s_waitcnt lgkmcnt(4)
	v_mfma_f32_16x16x32_bf16 v[52:55], v[204:207], v[176:179], v[52:55]
	v_add_f32_e32 v226, v224, v200
	v_exp_f32_e32 v225, v196
	v_mfma_f32_16x16x32_bf16 v[116:119], v[204:207], v[172:175], v[116:119]
	ds_read_b64_tr_b16 v[200:201], v241 offset:50176
	ds_read_b64_tr_b16 v[202:203], v241 offset:58368
	s_waitcnt lgkmcnt(4)
	v_mfma_f32_16x16x32_bf16 v[112:115], v[180:183], v[172:175], v[112:115]
	v_add_f32_e32 v196, v225, v221
	v_exp_f32_e32 v204, v197
	v_mfma_f32_16x16x32_bf16 v[48:51], v[180:183], v[176:179], v[48:51]
	ds_read_b64_tr_b16 v[180:181], v0 offset:51200
	ds_read_b64_tr_b16 v[182:183], v0 offset:59392
	s_waitcnt lgkmcnt(4)
	v_mfma_f32_16x16x32_bf16 v[44:47], v[184:187], v[176:179], v[44:47]
	v_add_f32_e32 v196, v204, v196
	v_exp_f32_e32 v205, v198
	v_mfma_f32_16x16x32_bf16 v[108:111], v[184:187], v[172:175], v[108:111]
	ds_read_b64_tr_b16 v[184:185], v229 offset:51200
	ds_read_b64_tr_b16 v[186:187], v229 offset:59392
	s_waitcnt lgkmcnt(4)
	v_mfma_f32_16x16x32_bf16 v[104:107], v[200:203], v[172:175], v[104:107]
	v_add_f32_e32 v207, v205, v196
	v_exp_f32_e32 v206, v199
	v_mfma_f32_16x16x32_bf16 v[40:43], v[200:203], v[176:179], v[40:43]
	ds_read_b64_tr_b16 v[196:197], v238 offset:51200
	ds_read_b64_tr_b16 v[198:199], v238 offset:59392
	s_waitcnt lgkmcnt(4)
	v_mfma_f32_16x16x32_bf16 v[36:39], v[180:183], v[176:179], v[36:39]
	v_add_f32_e32 v200, v206, v207
	v_exp_f32_e32 v192, v192
	v_mfma_f32_16x16x32_bf16 v[100:103], v[180:183], v[172:175], v[100:103]
	ds_read_b64_tr_b16 v[180:181], v241 offset:51200
	ds_read_b64_tr_b16 v[182:183], v241 offset:59392
	s_waitcnt lgkmcnt(4)
	v_mfma_f32_16x16x32_bf16 v[96:99], v[184:187], v[172:175], v[96:99]
	v_add_f32_e32 v201, v192, v226
	v_exp_f32_e32 v193, v193
	v_mfma_f32_16x16x32_bf16 v[32:35], v[184:187], v[176:179], v[32:35]
	ds_read_b64_tr_b16 v[184:185], v0 offset:52224
	ds_read_b64_tr_b16 v[186:187], v0 offset:60416
	s_waitcnt lgkmcnt(4)
	v_mfma_f32_16x16x32_bf16 v[28:31], v[196:199], v[176:179], v[28:31]
	v_exp_f32_e32 v0, v194
	v_add_f32_e32 v194, v193, v201
	v_mfma_f32_16x16x32_bf16 v[92:95], v[196:199], v[172:175], v[92:95]
	ds_read_b64_tr_b16 v[196:197], v229 offset:52224
	ds_read_b64_tr_b16 v[198:199], v229 offset:60416
	s_waitcnt lgkmcnt(4)
	v_mfma_f32_16x16x32_bf16 v[88:91], v[180:183], v[172:175], v[88:91]
	v_add_f32_e32 v194, v0, v194
	v_exp_f32_e32 v195, v195
	v_mfma_f32_16x16x32_bf16 v[24:27], v[180:183], v[176:179], v[24:27]
	ds_read_b64_tr_b16 v[180:181], v238 offset:52224
	ds_read_b64_tr_b16 v[182:183], v238 offset:60416
	s_waitcnt lgkmcnt(4)
	v_mfma_f32_16x16x32_bf16 v[20:23], v[184:187], v[176:179], v[20:23]
	v_exp_f32_e32 v201, v188
	v_add_f32_e32 v188, v195, v194
	v_mfma_f32_16x16x32_bf16 v[84:87], v[184:187], v[172:175], v[84:87]
	ds_read_b64_tr_b16 v[184:185], v241 offset:52224
	ds_read_b64_tr_b16 v[186:187], v241 offset:60416
	s_waitcnt lgkmcnt(4)
	v_mfma_f32_16x16x32_bf16 v[80:83], v[196:199], v[172:175], v[80:83]
	v_exp_f32_e32 v194, v189
	v_add_f32_e32 v189, v201, v200
	v_mfma_f32_16x16x32_bf16 v[16:19], v[196:199], v[176:179], v[16:19]
	s_waitcnt lgkmcnt(2)
	v_mfma_f32_16x16x32_bf16 v[12:15], v[180:183], v[176:179], v[12:15]
	v_add_f32_e32 v189, v194, v189
	v_exp_f32_e32 v190, v190
	v_mfma_f32_16x16x32_bf16 v[76:79], v[180:183], v[172:175], v[76:79]
	s_waitcnt lgkmcnt(0)
	v_mfma_f32_16x16x32_bf16 v[8:11], v[184:187], v[176:179], v[8:11]
	v_add_f32_e32 v176, v190, v189
	v_exp_f32_e32 v191, v191
	v_mfma_f32_16x16x32_bf16 v[72:75], v[184:187], v[172:175], v[72:75]
	s_cmp_lt_u32 s20, s73
	v_add_f32_e32 v172, v191, v176
	s_cselect_b64 vcc, -1, 0
	v_cndmask_b32_e32 v189, 0, v188, vcc
	v_cndmask_b32_e32 v188, 0, v172, vcc
	v_cvt_pk_bf16_f32 v184, v2, v3
	v_cvt_pk_bf16_f32 v185, v242, v243
	v_cvt_pk_bf16_f32 v186, v248, v249
	v_cvt_pk_bf16_f32 v187, v239, v250
	v_cvt_pk_bf16_f32 v180, v244, v245
	v_cvt_pk_bf16_f32 v181, v246, v247
	v_cvt_pk_bf16_f32 v182, v234, v235
	v_cvt_pk_bf16_f32 v183, v236, v237
	v_cvt_pk_bf16_f32 v176, v220, v222
	v_cvt_pk_bf16_f32 v177, v223, v224
	v_cvt_pk_bf16_f32 v178, v192, v193
	v_cvt_pk_bf16_f32 v179, v0, v195
	v_cvt_pk_bf16_f32 v172, v225, v204
	v_cvt_pk_bf16_f32 v173, v205, v206
	v_cvt_pk_bf16_f32 v174, v201, v194
	v_cvt_pk_bf16_f32 v175, v190, v191
	v_pk_add_f32 v[208:209], v[208:209], v[188:189]
